# phase B q/kv tiles: rotary table rows staged once per tile in idle GEMM LDS and read with ds_read_b128 (were 24 global fetches each behind vmcnt(0))
# speedup vs baseline: 1.0121x; 1.0076x over previous
; DI u16 f2bf(float x) { return (u16)(pk2(x, 0.f) & 0xffffu); }
; DI uint2 pk4(float a, float b, float c, float d) { uint2 o; o.x = pk2(a, b); o.y = pk2(c, d); return o; }
; DI void phaseB(int wv0, PP p, unsigned char* smem) {
;     ...
;       epi256(wv0, acc, brow, bcol, [&](int ai, int bj, int m, int n, int row, int col0, f32x4& v) {
;         const int sub = (pn - 2) * 2 + bj;
;         const bool dorope = (sub == 2 || sub == 4), transposed = (sub == 3 || sub == 5);
;         u16* dst = (u16*)(p->ws + OFF_KCIN + (size_t)sub * 8 * MB);
;         const int c128 = col0 & 127, g = c128 >> 6, d0 = c128 & 63;
;         const int b = row >> 13, sq = row & (S_ - 1);
;         f32x4 r = v;
;         if (dorope && n == 0 && ropewave) {
;           const int kq = ((lane >> 4) & 1) * 4;
;           const float4 c4 = *(const float4*)(rope + sq * 16 + kq), s4 = *(const float4*)(rope + sq * 16 + 8 + kq);
;           const float cc[4] = {c4.x, c4.y, c4.z, c4.w}, ss[4] = {s4.x, s4.y, s4.z, s4.w};
; #pragma unroll
;           for (int j = 0; j < 4; ++j) {
;             const float pr = __shfl_xor(v[j], 32);
;             r[j] = (lane & 32) ? (v[j] * cc[j] + pr * ss[j]) : (v[j] * cc[j] - pr * ss[j]);
;           }
;         }
;         if (transposed) {
; #pragma unroll
;           for (int j = 0; j < 4; ++j) dst[((size_t)((b * 2 + g) * 64 + d0 + j)) * S_ + sq] = f2bf(r[j]);
;         } else {
;           *(uint2*)(dst + ((size_t)(b * 2 + g) * S_ + sq) * 64 + d0) = pk4(r[0], r[1], r[2], r[3]);
;         }
;       });
.LBB0_207:
	s_andn2_b64 vcc, exec, s[4:5]
	s_cbranch_vccnz .LBB0_289
	s_and_b32 s4, s62, 0x1fff
	s_lshl_b32 s4, s4, 6
	v_lshlrev_b32_e32 v248, 5, v154
	v_and_b32_e32 v249, 16, v154
	v_sub_u32_e32 v250, v248, v249
	v_add_u32_e32 v250, s4, v250
	v_mov_b32_e32 v251, 0
	v_lshl_add_u64 v[252:253], v[134:135], 0, v[250:251]
	global_load_dwordx4 v[236:239], v[252:253], off
	global_load_dwordx4 v[240:243], v[252:253], off offset:16
	v_add_u32_e32 v248, 32, v248
	s_sub_i32 s5, 32, s4
	v_add_u32_e32 v250, s5, v249
	s_waitcnt vmcnt(0)
	ds_write_b128 v248, v[236:239]
	ds_write_b128 v248, v[240:243] offset:16
	s_waitcnt lgkmcnt(0)
	s_barrier
	s_add_i32 s95, s62, s74
	s_cmp_eq_u32 s66, 2
	s_cselect_b64 s[6:7], -1, 0
	s_cmp_lg_u32 s66, 2
	v_mov_b32_e32 v136, v154
	s_cselect_b64 s[4:5], -1, 0
	v_mov_b32_e32 v128, s95
	v_and_b32_e32 v148, 15, v136
	s_and_b64 s[64:65], s[24:25], s[4:5]
	v_bitop3_b32 v149, v148, s93, v128 bitop3:0xc8
	v_cndmask_b32_e64 v128, 0, 1, s[64:65]
	v_cmp_ne_u32_e64 s[4:5], 1, v128
	v_mov_b64_e32 v[130:131], v[126:127]
	s_andn2_b64 vcc, exec, s[64:65]
	v_lshlrev_b32_e32 v146, 6, v149
	v_mov_b64_e32 v[128:129], v[124:125]
	s_cbranch_vccnz .LBB0_210
	v_mov_b32_e32 v147, v133
	v_add_u32_e32 v138, v250, v146
	ds_read_b128 v[128:131], v138 offset:32
	s_nop 0
	ds_read_b128 v[138:141], v138
	ds_bpermute_b32 v142, v155, v124
	ds_bpermute_b32 v143, v155, v125
	ds_bpermute_b32 v144, v155, v126
	ds_bpermute_b32 v145, v155, v127
	s_waitcnt lgkmcnt(0)
	v_pk_mul_f32 v[128:129], v[128:129], v[142:143]
	v_pk_mul_f32 v[130:131], v[130:131], v[144:145]
	v_cndmask_b32_e64 v129, v129, -v129, s[2:3]
	v_cndmask_b32_e64 v131, v131, -v131, s[2:3]
	v_cndmask_b32_e64 v130, v130, -v130, s[2:3]
	v_cndmask_b32_e64 v128, v128, -v128, s[2:3]
	v_pk_fma_f32 v[130:131], v[126:127], v[140:141], v[130:131]
	v_pk_fma_f32 v[128:129], v[124:125], v[138:139], v[128:129]
.LBB0_210:
	s_lshl_b32 s70, s66, 1
	s_ashr_i32 s96, s95, 13
	s_add_i32 s10, s70, -4
	s_lshl_b32 s68, s96, 1
	s_lshl_b64 s[64:65], s[10:11], 23
	s_add_u32 s66, s79, s64
	s_addc_u32 s67, s80, s65
	s_or_b32 s64, s68, s78
	s_ashr_i32 s65, s64, 31
	s_lshl_b64 s[68:69], s[64:65], 20
	v_lshrrev_b32_e32 v132, 2, v136
	s_add_u32 s64, s66, s68
	v_and_or_b32 v159, v132, 12, s82
	s_addc_u32 s65, s67, s69
	v_lshlrev_b32_e32 v132, 7, v149
	v_cvt_pk_bf16_f32 v128, v128, v129
	v_cvt_pk_bf16_f32 v129, v130, v131
	v_lshl_add_u64 v[130:131], s[64:65], 0, v[132:133]
	v_lshlrev_b32_e32 v132, 1, v159
	v_lshl_add_u64 v[130:131], v[130:131], 0, v[132:133]
	global_store_dwordx2 v[130:131], v[128:129], off
	v_cvt_pk_bf16_f32 v128, v120, v121
	v_cvt_pk_bf16_f32 v129, v122, v123
	global_store_dwordx2 v[130:131], v[128:129], off offset:32
	v_or_b32_e32 v137, 16, v149
	v_mov_b64_e32 v[130:131], v[118:119]
	s_and_b64 vcc, exec, s[4:5]
	v_lshlrev_b32_e32 v144, 6, v137
	v_mov_b64_e32 v[128:129], v[116:117]
	s_cbranch_vccnz .LBB0_212
	v_mov_b32_e32 v145, v133
	v_add_u32_e32 v138, v250, v144
	ds_read_b128 v[128:131], v138 offset:32
	s_nop 0
	ds_read_b128 v[138:141], v138
	ds_bpermute_b32 v142, v155, v116
	ds_bpermute_b32 v143, v155, v117
	ds_bpermute_b32 v150, v155, v118
	ds_bpermute_b32 v151, v155, v119
	s_waitcnt lgkmcnt(0)
	v_pk_mul_f32 v[128:129], v[128:129], v[142:143]
	v_pk_mul_f32 v[130:131], v[130:131], v[150:151]
	v_cndmask_b32_e64 v129, v129, -v129, s[2:3]
	v_cndmask_b32_e64 v131, v131, -v131, s[2:3]
	v_cndmask_b32_e64 v130, v130, -v130, s[2:3]
	v_cndmask_b32_e64 v128, v128, -v128, s[2:3]
	v_pk_fma_f32 v[130:131], v[118:119], v[140:141], v[130:131]
	v_pk_fma_f32 v[128:129], v[116:117], v[138:139], v[128:129]
.LBB0_212:
	v_lshrrev_b16_e32 v136, 2, v136
	v_and_b32_e32 v138, 12, v136
	v_subrev_u16_e32 v138, s75, v138
	v_bitop3_b16 v136, v136, 16, 12 bitop3:0xec
	v_cvt_pk_bf16_f32 v128, v128, v129
	v_cvt_pk_bf16_f32 v129, v130, v131
	v_lshlrev_b32_e32 v130, 7, v137
	v_mov_b32_e32 v131, v133
	v_and_b32_e32 v158, 63, v138
	v_subrev_u16_e32 v140, s75, v136
	v_lshl_add_u64 v[130:131], s[64:65], 0, v[130:131]
	v_lshlrev_b32_e32 v138, 1, v158
	v_mov_b32_e32 v139, v133
	v_lshl_add_u64 v[136:137], v[130:131], 0, v[138:139]
	v_and_b32_e32 v157, 63, v140
	global_store_dwordx2 v[136:137], v[128:129], off
	v_lshlrev_b32_e32 v136, 1, v157
	v_mov_b32_e32 v137, v133
	v_cvt_pk_bf16_f32 v128, v112, v113
	v_cvt_pk_bf16_f32 v129, v114, v115
	v_lshl_add_u64 v[130:131], v[130:131], 0, v[136:137]
	global_store_dwordx2 v[130:131], v[128:129], off
	v_or_b32_e32 v137, 32, v149
	v_mov_b64_e32 v[130:131], v[110:111]
	s_and_b64 vcc, exec, s[4:5]
	v_lshlrev_b32_e32 v142, 6, v137
	v_mov_b64_e32 v[128:129], v[108:109]
	s_cbranch_vccnz .LBB0_214
	v_mov_b32_e32 v143, v133
	v_add_u32_e32 v140, v250, v142
	ds_read_b128 v[128:131], v140 offset:32
	ds_read_b128 v[150:153], v140
	ds_bpermute_b32 v140, v155, v108
	ds_bpermute_b32 v141, v155, v109
	ds_bpermute_b32 v160, v155, v110
	ds_bpermute_b32 v161, v155, v111
	s_waitcnt lgkmcnt(0)
	v_pk_mul_f32 v[128:129], v[128:129], v[140:141]
	v_pk_mul_f32 v[130:131], v[130:131], v[160:161]
	v_cndmask_b32_e64 v129, v129, -v129, s[2:3]
	v_cndmask_b32_e64 v131, v131, -v131, s[2:3]
	v_cndmask_b32_e64 v130, v130, -v130, s[2:3]
	v_cndmask_b32_e64 v128, v128, -v128, s[2:3]
	v_pk_fma_f32 v[130:131], v[110:111], v[152:153], v[130:131]
	v_pk_fma_f32 v[128:129], v[108:109], v[150:151], v[128:129]
.LBB0_214:
	s_nop 0
	v_cvt_pk_bf16_f32 v128, v128, v129
	v_cvt_pk_bf16_f32 v129, v130, v131
	v_lshlrev_b32_e32 v130, 7, v137
	v_mov_b32_e32 v131, v133
	v_lshl_add_u64 v[130:131], s[64:65], 0, v[130:131]
	v_lshl_add_u64 v[130:131], v[130:131], 0, v[132:133]
	global_store_dwordx2 v[130:131], v[128:129], off
	v_cvt_pk_bf16_f32 v128, v104, v105
	v_cvt_pk_bf16_f32 v129, v106, v107
	global_store_dwordx2 v[130:131], v[128:129], off offset:32
	v_or_b32_e32 v137, 48, v149
	v_mov_b64_e32 v[130:131], v[102:103]
	s_and_b64 vcc, exec, s[4:5]
	v_lshlrev_b32_e32 v140, 6, v137
	v_mov_b64_e32 v[128:129], v[100:101]
	s_cbranch_vccnz .LBB0_216
	v_mov_b32_e32 v141, v133
	v_add_u32_e32 v150, v250, v140
	ds_read_b128 v[128:131], v150 offset:32
	s_nop 0
	ds_read_b128 v[150:153], v150
	ds_bpermute_b32 v160, v155, v100
	ds_bpermute_b32 v161, v155, v101
	ds_bpermute_b32 v162, v155, v102
	ds_bpermute_b32 v163, v155, v103
	s_waitcnt lgkmcnt(0)
	v_pk_mul_f32 v[128:129], v[128:129], v[160:161]
	v_pk_mul_f32 v[130:131], v[130:131], v[162:163]
	v_cndmask_b32_e64 v129, v129, -v129, s[2:3]
	v_cndmask_b32_e64 v131, v131, -v131, s[2:3]
	v_cndmask_b32_e64 v130, v130, -v130, s[2:3]
	v_cndmask_b32_e64 v128, v128, -v128, s[2:3]
	v_pk_fma_f32 v[130:131], v[102:103], v[152:153], v[130:131]
	v_pk_fma_f32 v[128:129], v[100:101], v[150:151], v[128:129]

; DI u16 f2bf(float x) { return (u16)(pk2(x, 0.f) & 0xffffu); }
; DI uint2 pk4(float a, float b, float c, float d) { uint2 o; o.x = pk2(a, b); o.y = pk2(c, d); return o; }
; DI void phaseB(int wv0, PP p, unsigned char* smem) {
;     ...
;       epi256(wv0, acc, brow, bcol, [&](int ai, int bj, int m, int n, int row, int col0, f32x4& v) {
;         const int sub = (pn - 2) * 2 + bj;
;         const bool dorope = (sub == 2 || sub == 4), transposed = (sub == 3 || sub == 5);
;         u16* dst = (u16*)(p->ws + OFF_KCIN + (size_t)sub * 8 * MB);
;         const int c128 = col0 & 127, g = c128 >> 6, d0 = c128 & 63;
;         const int b = row >> 13, sq = row & (S_ - 1);
;         f32x4 r = v;
;         if (dorope && n == 0 && ropewave) {
;           const int kq = ((lane >> 4) & 1) * 4;
;           const float4 c4 = *(const float4*)(rope + sq * 16 + kq), s4 = *(const float4*)(rope + sq * 16 + 8 + kq);
;           const float cc[4] = {c4.x, c4.y, c4.z, c4.w}, ss[4] = {s4.x, s4.y, s4.z, s4.w};
; #pragma unroll
;           for (int j = 0; j < 4; ++j) {
;             const float pr = __shfl_xor(v[j], 32);
;             r[j] = (lane & 32) ? (v[j] * cc[j] + pr * ss[j]) : (v[j] * cc[j] - pr * ss[j]);
;           }
;         }
;         if (transposed) {
; #pragma unroll
;           for (int j = 0; j < 4; ++j) dst[((size_t)((b * 2 + g) * 64 + d0 + j)) * S_ + sq] = f2bf(r[j]);
;         } else {
;           *(uint2*)(dst + ((size_t)(b * 2 + g) * S_ + sq) * 64 + d0) = pk4(r[0], r[1], r[2], r[3]);
;         }
;       });
.LBB0_248:
	v_or_b32_e32 v140, s95, v148
	v_add_u32_e32 v137, 0x80, v140
	v_and_b32_e32 v166, 0x1fcf, v137
	v_mov_b64_e32 v[130:131], v[62:63]
	s_and_b64 vcc, exec, s[4:5]
	v_lshlrev_b32_e32 v150, 6, v166
	v_mov_b64_e32 v[128:129], v[60:61]
	s_cbranch_vccnz .LBB0_250
	v_mov_b32_e32 v151, v133
	v_add_u32_e32 v142, v250, v150
	ds_read_b128 v[128:131], v142 offset:32
	s_nop 0
	ds_read_b128 v[142:145], v142
	ds_bpermute_b32 v146, v155, v60
	ds_bpermute_b32 v147, v155, v61
	ds_bpermute_b32 v148, v155, v62
	ds_bpermute_b32 v149, v155, v63
	s_waitcnt lgkmcnt(0)
	v_pk_mul_f32 v[128:129], v[128:129], v[146:147]
	v_pk_mul_f32 v[130:131], v[130:131], v[148:149]
	v_cndmask_b32_e64 v129, v129, -v129, s[2:3]
	v_cndmask_b32_e64 v131, v131, -v131, s[2:3]
	v_cndmask_b32_e64 v130, v130, -v130, s[2:3]
	v_cndmask_b32_e64 v128, v128, -v128, s[2:3]
	v_pk_fma_f32 v[130:131], v[62:63], v[144:145], v[130:131]
	v_pk_fma_f32 v[128:129], v[60:61], v[142:143], v[128:129]
.LBB0_250:
	v_ashrrev_i32_e32 v167, 13, v137
	v_cvt_pk_bf16_f32 v128, v128, v129
	v_cvt_pk_bf16_f32 v129, v130, v131
	v_lshl_or_b32 v130, v167, 1, s78
	v_ashrrev_i32_e32 v131, 31, v130
	v_lshlrev_b64 v[152:153], 20, v[130:131]
	v_lshl_add_u64 v[130:131], s[66:67], 0, v[152:153]
	v_lshlrev_b32_e32 v142, 7, v166
	v_mov_b32_e32 v143, v133
	v_lshl_add_u64 v[130:131], v[130:131], 0, v[142:143]
	v_lshl_add_u64 v[130:131], v[130:131], 0, v[132:133]
	global_store_dwordx2 v[130:131], v[128:129], off
	v_cvt_pk_bf16_f32 v128, v56, v57
	v_cvt_pk_bf16_f32 v129, v58, v59
	v_add_u32_e32 v137, 0x90, v140
	global_store_dwordx2 v[130:131], v[128:129], off offset:32
	v_and_b32_e32 v164, 0x1fdf, v137
	v_mov_b64_e32 v[130:131], v[54:55]
	s_and_b64 vcc, exec, s[4:5]
	v_lshlrev_b32_e32 v146, 6, v164
	v_mov_b64_e32 v[128:129], v[52:53]
	s_cbranch_vccnz .LBB0_252
	v_mov_b32_e32 v147, v133
	v_add_u32_e32 v142, v250, v146
	ds_read_b128 v[128:131], v142 offset:32
	s_nop 0
	ds_read_b128 v[142:145], v142
	ds_bpermute_b32 v148, v155, v52
	ds_bpermute_b32 v149, v155, v53
	ds_bpermute_b32 v162, v155, v54
	ds_bpermute_b32 v163, v155, v55
	s_waitcnt lgkmcnt(0)
	v_pk_mul_f32 v[128:129], v[128:129], v[148:149]
	v_pk_mul_f32 v[130:131], v[130:131], v[162:163]
	v_cndmask_b32_e64 v129, v129, -v129, s[2:3]
	v_cndmask_b32_e64 v131, v131, -v131, s[2:3]
	v_cndmask_b32_e64 v130, v130, -v130, s[2:3]
	v_cndmask_b32_e64 v128, v128, -v128, s[2:3]
	v_pk_fma_f32 v[130:131], v[54:55], v[144:145], v[130:131]
	v_pk_fma_f32 v[128:129], v[52:53], v[142:143], v[128:129]
.LBB0_252:
	v_ashrrev_i32_e32 v165, 13, v137
	v_cvt_pk_bf16_f32 v128, v128, v129
	v_cvt_pk_bf16_f32 v129, v130, v131
	v_lshl_or_b32 v130, v165, 1, s78
	v_ashrrev_i32_e32 v131, 31, v130
	v_lshlrev_b64 v[148:149], 20, v[130:131]
	v_lshl_add_u64 v[130:131], s[66:67], 0, v[148:149]
	v_lshlrev_b32_e32 v142, 7, v164
	v_mov_b32_e32 v143, v133
	v_lshl_add_u64 v[130:131], v[130:131], 0, v[142:143]
	v_mov_b32_e32 v139, v133
	v_lshl_add_u64 v[142:143], v[130:131], 0, v[138:139]
	v_mov_b32_e32 v137, v133
	global_store_dwordx2 v[142:143], v[128:129], off
	v_cvt_pk_bf16_f32 v128, v48, v49
	v_cvt_pk_bf16_f32 v129, v50, v51
	v_lshl_add_u64 v[130:131], v[130:131], 0, v[136:137]
	global_store_dwordx2 v[130:131], v[128:129], off
	v_add_u32_e32 v137, 0xa0, v140
	v_and_b32_e32 v162, 0x1fef, v137
	v_mov_b64_e32 v[130:131], v[46:47]
	s_and_b64 vcc, exec, s[4:5]
	v_lshlrev_b32_e32 v142, 6, v162
	v_mov_b64_e32 v[128:129], v[44:45]
	s_cbranch_vccnz .LBB0_254
	v_mov_b32_e32 v143, v133
	v_add_u32_e32 v144, v250, v142
	ds_read_b128 v[128:131], v144 offset:32
	ds_read_b128 v[168:171], v144
	ds_bpermute_b32 v144, v155, v44
	ds_bpermute_b32 v145, v155, v45
	ds_bpermute_b32 v172, v155, v46
	ds_bpermute_b32 v173, v155, v47
	s_waitcnt lgkmcnt(0)
	v_pk_mul_f32 v[128:129], v[128:129], v[144:145]
	v_pk_mul_f32 v[130:131], v[130:131], v[172:173]
	v_cndmask_b32_e64 v129, v129, -v129, s[2:3]
	v_cndmask_b32_e64 v131, v131, -v131, s[2:3]
	v_cndmask_b32_e64 v130, v130, -v130, s[2:3]
	v_cndmask_b32_e64 v128, v128, -v128, s[2:3]
	v_pk_fma_f32 v[130:131], v[46:47], v[170:171], v[130:131]
	v_pk_fma_f32 v[128:129], v[44:45], v[168:169], v[128:129]
.LBB0_254:
	v_ashrrev_i32_e32 v163, 13, v137
	v_cvt_pk_bf16_f32 v128, v128, v129
	v_cvt_pk_bf16_f32 v129, v130, v131
	v_lshl_or_b32 v130, v163, 1, s78
	v_ashrrev_i32_e32 v131, 31, v130
	v_lshlrev_b64 v[144:145], 20, v[130:131]
	v_lshl_add_u64 v[130:131], s[66:67], 0, v[144:145]
	v_lshlrev_b32_e32 v168, 7, v162
	v_mov_b32_e32 v169, v133
	v_lshl_add_u64 v[130:131], v[130:131], 0, v[168:169]
	v_lshl_add_u64 v[130:131], v[130:131], 0, v[132:133]
	global_store_dwordx2 v[130:131], v[128:129], off
	v_cvt_pk_bf16_f32 v128, v40, v41
	v_cvt_pk_bf16_f32 v129, v42, v43
	v_add_u32_e32 v137, 0xb0, v140
	global_store_dwordx2 v[130:131], v[128:129], off offset:32
	v_and_b32_e32 v161, 0x1fff, v137
	v_mov_b64_e32 v[130:131], v[38:39]
	s_and_b64 vcc, exec, s[4:5]
	v_lshlrev_b32_e32 v140, 6, v161
	v_mov_b64_e32 v[128:129], v[36:37]
	s_cbranch_vccnz .LBB0_256
	v_mov_b32_e32 v141, v133
	v_add_u32_e32 v168, v250, v140
	ds_read_b128 v[128:131], v168 offset:32
	s_nop 0
	ds_read_b128 v[168:171], v168
	ds_bpermute_b32 v172, v155, v36
	ds_bpermute_b32 v173, v155, v37
	ds_bpermute_b32 v174, v155, v38
	ds_bpermute_b32 v175, v155, v39
	s_waitcnt lgkmcnt(0)
	v_pk_mul_f32 v[128:129], v[128:129], v[172:173]
	v_pk_mul_f32 v[130:131], v[130:131], v[174:175]
	v_cndmask_b32_e64 v129, v129, -v129, s[2:3]
	v_cndmask_b32_e64 v131, v131, -v131, s[2:3]
	v_cndmask_b32_e64 v130, v130, -v130, s[2:3]
	v_cndmask_b32_e64 v128, v128, -v128, s[2:3]
	v_pk_fma_f32 v[130:131], v[38:39], v[170:171], v[130:131]
	v_pk_fma_f32 v[128:129], v[36:37], v[168:169], v[128:129]

; DI uint2 pk4(float a, float b, float c, float d) { uint2 o; o.x = pk2(a, b); o.y = pk2(c, d); return o; }
; DI void phaseB(int wv0, PP p, unsigned char* smem) {
;     ...
;       epi256(wv0, acc, brow, bcol, [&](int ai, int bj, int m, int n, int row, int col0, f32x4& v) {
;         f32x4 r = v;
;         if (n == 0 && ropewave) {
;           const int pos = row & (S_ - 1), kq = ((lane >> 4) & 1) * 4;
;           const float4 c4 = *(const float4*)(rope + pos * 16 + kq), s4 = *(const float4*)(rope + pos * 16 + 8 + kq);
;           const float cc[4] = {c4.x, c4.y, c4.z, c4.w}, ss[4] = {s4.x, s4.y, s4.z, s4.w};
; #pragma unroll
;           for (int j = 0; j < 4; ++j) {
;             const float pr = __shfl_xor(v[j], 32);
;             r[j] = (lane & 32) ? (v[j] * cc[j] + pr * ss[j]) : (v[j] * cc[j] - pr * ss[j]);
;           }
;         }
;         *(uint2*)(QR + (size_t)row * 512 + col0) = pk4(v[0] * QSCALE, v[1] * QSCALE, v[2] * QSCALE, v[3] * QSCALE);
;         *(uint2*)(QO + (size_t)row * 512 + col0) = pk4(r[0] * QSCALE, r[1] * QSCALE, r[2] * QSCALE, r[3] * QSCALE);
;       });
.LBB0_290:
	s_and_b32 s4, s62, 0x1fff
	s_lshl_b32 s4, s4, 6
	v_lshlrev_b32_e32 v248, 5, v154
	v_and_b32_e32 v249, 16, v154
	v_sub_u32_e32 v250, v248, v249
	v_add_u32_e32 v250, s4, v250
	v_mov_b32_e32 v251, 0
	v_lshl_add_u64 v[252:253], v[134:135], 0, v[250:251]
	global_load_dwordx4 v[236:239], v[252:253], off
	global_load_dwordx4 v[240:243], v[252:253], off offset:16
	v_add_u32_e32 v248, 32, v248
	s_sub_i32 s5, 32, s4
	v_add_u32_e32 v250, s5, v249
	s_waitcnt vmcnt(0)
	ds_write_b128 v248, v[236:239]
	ds_write_b128 v248, v[240:243] offset:16
	s_waitcnt lgkmcnt(0)
	s_barrier
	v_mov_b32_e32 v129, v154
	s_add_i32 s4, s62, s74
	s_and_b64 vcc, exec, s[30:31]
	v_and_or_b32 v128, v129, 15, s4
	v_lshlrev_b32_e32 v130, 4, v128
	v_and_b32_e32 v130, 0x1fcf0, v130
	s_mov_b64 s[4:5], -1
	v_lshlrev_b32_e32 v130, 2, v130
	s_cbranch_vccz .LBB0_292
	v_mov_b32_e32 v131, v133
	v_add_u32_e32 v140, v250, v130
	ds_read_b128 v[136:139], v140 offset:32
	s_nop 0
	ds_read_b128 v[140:143], v140
	ds_bpermute_b32 v144, v155, v124
	ds_bpermute_b32 v145, v155, v125
	ds_bpermute_b32 v146, v155, v126
	ds_bpermute_b32 v147, v155, v127
	s_mov_b64 s[4:5], 0
	s_waitcnt lgkmcnt(0)
	v_pk_mul_f32 v[136:137], v[136:137], v[144:145]
	v_pk_mul_f32 v[138:139], v[138:139], v[146:147]
	v_cndmask_b32_e64 v137, v137, -v137, s[2:3]
	v_cndmask_b32_e64 v136, v136, -v136, s[2:3]
	v_cndmask_b32_e64 v139, v139, -v139, s[2:3]
	v_cndmask_b32_e64 v138, v138, -v138, s[2:3]
	v_pk_fma_f32 v[136:137], v[124:125], v[140:141], v[136:137]
	v_pk_fma_f32 v[138:139], v[126:127], v[142:143], v[138:139]

; DI uint2 pk4(float a, float b, float c, float d) { uint2 o; o.x = pk2(a, b); o.y = pk2(c, d); return o; }
; DI void phaseB(int wv0, PP p, unsigned char* smem) {
;     ...
;       epi256(wv0, acc, brow, bcol, [&](int ai, int bj, int m, int n, int row, int col0, f32x4& v) {
;         f32x4 r = v;
;         if (n == 0 && ropewave) {
;           const int pos = row & (S_ - 1), kq = ((lane >> 4) & 1) * 4;
;           const float4 c4 = *(const float4*)(rope + pos * 16 + kq), s4 = *(const float4*)(rope + pos * 16 + 8 + kq);
;           const float cc[4] = {c4.x, c4.y, c4.z, c4.w}, ss[4] = {s4.x, s4.y, s4.z, s4.w};
; #pragma unroll
;           for (int j = 0; j < 4; ++j) {
;             const float pr = __shfl_xor(v[j], 32);
;             r[j] = (lane & 32) ? (v[j] * cc[j] + pr * ss[j]) : (v[j] * cc[j] - pr * ss[j]);
;           }
;         }
;         *(uint2*)(QR + (size_t)row * 512 + col0) = pk4(v[0] * QSCALE, v[1] * QSCALE, v[2] * QSCALE, v[3] * QSCALE);
;         *(uint2*)(QO + (size_t)row * 512 + col0) = pk4(r[0] * QSCALE, r[1] * QSCALE, r[2] * QSCALE, r[3] * QSCALE);
.LBB0_294:
	v_lshrrev_b32_e32 v129, 2, v129
	v_and_or_b32 v129, v129, 12, s77
	v_or_b32_e32 v131, s63, v129
	v_ashrrev_i32_e32 v129, 31, v128
	v_pk_mul_f32 v[126:127], v[126:127], s[60:61] op_sel_hi:[1,0]
	v_pk_mul_f32 v[124:125], v[124:125], s[60:61] op_sel_hi:[1,0]
	v_cvt_pk_bf16_f32 v141, v126, v127
	v_lshlrev_b64 v[126:127], 10, v[128:129]
	v_cvt_pk_bf16_f32 v140, v124, v125
	v_lshl_add_u64 v[124:125], s[26:27], 0, v[126:127]
	v_lshlrev_b32_e32 v132, 1, v131
	v_pk_mul_f32 v[136:137], v[136:137], s[60:61] op_sel_hi:[1,0]
	v_pk_mul_f32 v[138:139], v[138:139], s[60:61] op_sel_hi:[1,0]
	v_lshl_add_u64 v[126:127], s[28:29], 0, v[126:127]
	v_pk_mul_f32 v[120:121], v[120:121], s[60:61] op_sel_hi:[1,0]
	v_pk_mul_f32 v[122:123], v[122:123], s[60:61] op_sel_hi:[1,0]
	v_lshl_add_u64 v[124:125], v[124:125], 0, v[132:133]
	v_cvt_pk_bf16_f32 v136, v136, v137
	v_cvt_pk_bf16_f32 v137, v138, v139
	v_lshl_add_u64 v[126:127], v[126:127], 0, v[132:133]
	v_cvt_pk_bf16_f32 v120, v120, v121
	v_cvt_pk_bf16_f32 v121, v122, v123
	v_or_b32_e32 v122, 16, v128
	global_store_dwordx2 v[124:125], v[140:141], off
	global_store_dwordx2 v[126:127], v[136:137], off
	global_store_dwordx2 v[124:125], v[120:121], off offset:32
	global_store_dwordx2 v[126:127], v[120:121], off offset:32
	v_lshlrev_b32_e32 v120, 4, v122
	v_and_b32_e32 v120, 0x1fff0, v120
	s_mov_b64 s[4:5], -1
	s_and_b64 vcc, exec, s[30:31]
	v_lshlrev_b32_e32 v120, 2, v120
	s_cbranch_vccz .LBB0_296
	v_mov_b32_e32 v121, v133
	v_add_u32_e32 v140, v250, v120
	ds_read_b128 v[136:139], v140 offset:32
	s_nop 0
	ds_read_b128 v[140:143], v140
	ds_bpermute_b32 v144, v155, v116
	ds_bpermute_b32 v145, v155, v117
	ds_bpermute_b32 v146, v155, v118
	ds_bpermute_b32 v147, v155, v119
	s_mov_b64 s[4:5], 0
	s_waitcnt lgkmcnt(0)
	v_pk_mul_f32 v[136:137], v[136:137], v[144:145]
	v_pk_mul_f32 v[138:139], v[138:139], v[146:147]
	v_cndmask_b32_e64 v137, v137, -v137, s[2:3]
	v_cndmask_b32_e64 v136, v136, -v136, s[2:3]
	v_cndmask_b32_e64 v139, v139, -v139, s[2:3]
	v_cndmask_b32_e64 v138, v138, -v138, s[2:3]
	v_pk_fma_f32 v[136:137], v[116:117], v[140:141], v[136:137]
	v_pk_fma_f32 v[138:139], v[118:119], v[142:143], v[138:139]

; DI uint2 pk4(float a, float b, float c, float d) { uint2 o; o.x = pk2(a, b); o.y = pk2(c, d); return o; }
; DI void phaseB(int wv0, PP p, unsigned char* smem) {
;     ...
;       epi256(wv0, acc, brow, bcol, [&](int ai, int bj, int m, int n, int row, int col0, f32x4& v) {
;         f32x4 r = v;
;         if (n == 0 && ropewave) {
;           const int pos = row & (S_ - 1), kq = ((lane >> 4) & 1) * 4;
;           const float4 c4 = *(const float4*)(rope + pos * 16 + kq), s4 = *(const float4*)(rope + pos * 16 + 8 + kq);
;           const float cc[4] = {c4.x, c4.y, c4.z, c4.w}, ss[4] = {s4.x, s4.y, s4.z, s4.w};
; #pragma unroll
;           for (int j = 0; j < 4; ++j) {
;             const float pr = __shfl_xor(v[j], 32);
;             r[j] = (lane & 32) ? (v[j] * cc[j] + pr * ss[j]) : (v[j] * cc[j] - pr * ss[j]);
;           }
;         }
;         *(uint2*)(QR + (size_t)row * 512 + col0) = pk4(v[0] * QSCALE, v[1] * QSCALE, v[2] * QSCALE, v[3] * QSCALE);
;         *(uint2*)(QO + (size_t)row * 512 + col0) = pk4(r[0] * QSCALE, r[1] * QSCALE, r[2] * QSCALE, r[3] * QSCALE);
.LBB0_298:
	v_ashrrev_i32_e32 v123, 31, v122
	v_pk_mul_f32 v[118:119], v[118:119], s[60:61] op_sel_hi:[1,0]
	v_pk_mul_f32 v[116:117], v[116:117], s[60:61] op_sel_hi:[1,0]
	v_cvt_pk_bf16_f32 v141, v118, v119
	v_lshlrev_b64 v[118:119], 10, v[122:123]
	v_cvt_pk_bf16_f32 v140, v116, v117
	v_lshl_add_u64 v[116:117], s[26:27], 0, v[118:119]
	v_pk_mul_f32 v[122:123], v[136:137], s[60:61] op_sel_hi:[1,0]
	v_pk_mul_f32 v[136:137], v[138:139], s[60:61] op_sel_hi:[1,0]
	v_lshl_add_u64 v[118:119], s[28:29], 0, v[118:119]
	v_pk_mul_f32 v[112:113], v[112:113], s[60:61] op_sel_hi:[1,0]
	v_pk_mul_f32 v[114:115], v[114:115], s[60:61] op_sel_hi:[1,0]
	v_lshl_add_u64 v[116:117], v[116:117], 0, v[132:133]
	v_cvt_pk_bf16_f32 v122, v122, v123
	v_cvt_pk_bf16_f32 v123, v136, v137
	v_lshl_add_u64 v[118:119], v[118:119], 0, v[132:133]
	v_cvt_pk_bf16_f32 v112, v112, v113
	v_cvt_pk_bf16_f32 v113, v114, v115
	global_store_dwordx2 v[116:117], v[140:141], off
	global_store_dwordx2 v[118:119], v[122:123], off
	global_store_dwordx2 v[116:117], v[112:113], off offset:32
	global_store_dwordx2 v[118:119], v[112:113], off offset:32
	v_or_b32_e32 v114, 32, v128
	v_lshlrev_b32_e32 v112, 4, v114
	v_and_b32_e32 v112, 0x1fff0, v112
	s_mov_b64 s[4:5], -1
	s_and_b64 vcc, exec, s[30:31]
	v_lshlrev_b32_e32 v112, 2, v112
	s_cbranch_vccz .LBB0_300
	v_mov_b32_e32 v113, v133
	v_add_u32_e32 v122, v250, v112
	ds_read_b128 v[136:139], v122 offset:32
	ds_read_b128 v[140:143], v122
	ds_bpermute_b32 v122, v155, v108
	ds_bpermute_b32 v123, v155, v109
	ds_bpermute_b32 v144, v155, v110
	ds_bpermute_b32 v145, v155, v111
	s_mov_b64 s[4:5], 0
	s_waitcnt lgkmcnt(0)
	v_pk_mul_f32 v[122:123], v[136:137], v[122:123]
	v_pk_mul_f32 v[136:137], v[138:139], v[144:145]
	v_cndmask_b32_e64 v123, v123, -v123, s[2:3]
	v_cndmask_b32_e64 v122, v122, -v122, s[2:3]
	v_cndmask_b32_e64 v137, v137, -v137, s[2:3]
	v_cndmask_b32_e64 v136, v136, -v136, s[2:3]
	v_pk_fma_f32 v[122:123], v[108:109], v[140:141], v[122:123]
	v_pk_fma_f32 v[136:137], v[110:111], v[142:143], v[136:137]

; DI uint2 pk4(float a, float b, float c, float d) { uint2 o; o.x = pk2(a, b); o.y = pk2(c, d); return o; }
; DI void phaseB(int wv0, PP p, unsigned char* smem) {
;     ...
;       epi256(wv0, acc, brow, bcol, [&](int ai, int bj, int m, int n, int row, int col0, f32x4& v) {
;         f32x4 r = v;
;         if (n == 0 && ropewave) {
;           const int pos = row & (S_ - 1), kq = ((lane >> 4) & 1) * 4;
;           const float4 c4 = *(const float4*)(rope + pos * 16 + kq), s4 = *(const float4*)(rope + pos * 16 + 8 + kq);
;           const float cc[4] = {c4.x, c4.y, c4.z, c4.w}, ss[4] = {s4.x, s4.y, s4.z, s4.w};
; #pragma unroll
;           for (int j = 0; j < 4; ++j) {
;             const float pr = __shfl_xor(v[j], 32);
;             r[j] = (lane & 32) ? (v[j] * cc[j] + pr * ss[j]) : (v[j] * cc[j] - pr * ss[j]);
;           }
;         }
;         *(uint2*)(QR + (size_t)row * 512 + col0) = pk4(v[0] * QSCALE, v[1] * QSCALE, v[2] * QSCALE, v[3] * QSCALE);
;         *(uint2*)(QO + (size_t)row * 512 + col0) = pk4(r[0] * QSCALE, r[1] * QSCALE, r[2] * QSCALE, r[3] * QSCALE);
.LBB0_302:
	v_ashrrev_i32_e32 v115, 31, v114
	v_pk_mul_f32 v[110:111], v[110:111], s[60:61] op_sel_hi:[1,0]
	v_pk_mul_f32 v[108:109], v[108:109], s[60:61] op_sel_hi:[1,0]
	v_cvt_pk_bf16_f32 v139, v110, v111
	v_lshlrev_b64 v[110:111], 10, v[114:115]
	v_cvt_pk_bf16_f32 v138, v108, v109
	v_lshl_add_u64 v[108:109], s[26:27], 0, v[110:111]
	v_pk_mul_f32 v[114:115], v[122:123], s[60:61] op_sel_hi:[1,0]
	v_pk_mul_f32 v[122:123], v[136:137], s[60:61] op_sel_hi:[1,0]
	v_lshl_add_u64 v[110:111], s[28:29], 0, v[110:111]
	v_pk_mul_f32 v[104:105], v[104:105], s[60:61] op_sel_hi:[1,0]
	v_pk_mul_f32 v[106:107], v[106:107], s[60:61] op_sel_hi:[1,0]
	v_lshl_add_u64 v[108:109], v[108:109], 0, v[132:133]
	v_cvt_pk_bf16_f32 v114, v114, v115
	v_cvt_pk_bf16_f32 v115, v122, v123
	v_lshl_add_u64 v[110:111], v[110:111], 0, v[132:133]
	v_cvt_pk_bf16_f32 v104, v104, v105
	v_cvt_pk_bf16_f32 v105, v106, v107
	v_or_b32_e32 v106, 48, v128
	global_store_dwordx2 v[108:109], v[138:139], off
	global_store_dwordx2 v[110:111], v[114:115], off
	global_store_dwordx2 v[108:109], v[104:105], off offset:32
	global_store_dwordx2 v[110:111], v[104:105], off offset:32
	v_lshlrev_b32_e32 v104, 4, v106
	v_and_b32_e32 v104, 0x1fff0, v104
	s_mov_b64 s[4:5], -1
	s_and_b64 vcc, exec, s[30:31]
	v_lshlrev_b32_e32 v104, 2, v104
	s_cbranch_vccz .LBB0_304
	v_mov_b32_e32 v105, v133
	v_add_u32_e32 v114, v250, v104
	ds_read_b128 v[136:139], v114 offset:32
	ds_read_b128 v[140:143], v114
	ds_bpermute_b32 v114, v155, v100
	ds_bpermute_b32 v115, v155, v101
	ds_bpermute_b32 v122, v155, v102
	ds_bpermute_b32 v123, v155, v103
	s_mov_b64 s[4:5], 0
	s_waitcnt lgkmcnt(0)
	v_pk_mul_f32 v[114:115], v[136:137], v[114:115]
	v_pk_mul_f32 v[122:123], v[138:139], v[122:123]
	v_cndmask_b32_e64 v115, v115, -v115, s[2:3]
	v_cndmask_b32_e64 v114, v114, -v114, s[2:3]
	v_cndmask_b32_e64 v123, v123, -v123, s[2:3]
	v_cndmask_b32_e64 v122, v122, -v122, s[2:3]
	v_pk_fma_f32 v[114:115], v[100:101], v[140:141], v[114:115]
	v_pk_fma_f32 v[122:123], v[102:103], v[142:143], v[122:123]

; DI uint2 pk4(float a, float b, float c, float d) { uint2 o; o.x = pk2(a, b); o.y = pk2(c, d); return o; }
; DI void phaseB(int wv0, PP p, unsigned char* smem) {
;     ...
;       epi256(wv0, acc, brow, bcol, [&](int ai, int bj, int m, int n, int row, int col0, f32x4& v) {
;         f32x4 r = v;
;         if (n == 0 && ropewave) {
;           const int pos = row & (S_ - 1), kq = ((lane >> 4) & 1) * 4;
;           const float4 c4 = *(const float4*)(rope + pos * 16 + kq), s4 = *(const float4*)(rope + pos * 16 + 8 + kq);
;           const float cc[4] = {c4.x, c4.y, c4.z, c4.w}, ss[4] = {s4.x, s4.y, s4.z, s4.w};
; #pragma unroll
;           for (int j = 0; j < 4; ++j) {
;             const float pr = __shfl_xor(v[j], 32);
;             r[j] = (lane & 32) ? (v[j] * cc[j] + pr * ss[j]) : (v[j] * cc[j] - pr * ss[j]);
;           }
;         }
;         *(uint2*)(QR + (size_t)row * 512 + col0) = pk4(v[0] * QSCALE, v[1] * QSCALE, v[2] * QSCALE, v[3] * QSCALE);
;         *(uint2*)(QO + (size_t)row * 512 + col0) = pk4(r[0] * QSCALE, r[1] * QSCALE, r[2] * QSCALE, r[3] * QSCALE);
.LBB0_306:
	v_ashrrev_i32_e32 v107, 31, v106
	v_pk_mul_f32 v[102:103], v[102:103], s[60:61] op_sel_hi:[1,0]
	v_pk_mul_f32 v[100:101], v[100:101], s[60:61] op_sel_hi:[1,0]
	v_cvt_pk_bf16_f32 v137, v102, v103
	v_lshlrev_b64 v[102:103], 10, v[106:107]
	v_cvt_pk_bf16_f32 v136, v100, v101
	v_lshl_add_u64 v[100:101], s[26:27], 0, v[102:103]
	v_pk_mul_f32 v[106:107], v[114:115], s[60:61] op_sel_hi:[1,0]
	v_pk_mul_f32 v[114:115], v[122:123], s[60:61] op_sel_hi:[1,0]
	v_lshl_add_u64 v[102:103], s[28:29], 0, v[102:103]
	v_pk_mul_f32 v[96:97], v[96:97], s[60:61] op_sel_hi:[1,0]
	v_pk_mul_f32 v[98:99], v[98:99], s[60:61] op_sel_hi:[1,0]
	v_lshl_add_u64 v[100:101], v[100:101], 0, v[132:133]
	v_cvt_pk_bf16_f32 v106, v106, v107
	v_cvt_pk_bf16_f32 v107, v114, v115
	v_lshl_add_u64 v[102:103], v[102:103], 0, v[132:133]
	v_cvt_pk_bf16_f32 v96, v96, v97
	v_cvt_pk_bf16_f32 v97, v98, v99
	global_store_dwordx2 v[100:101], v[136:137], off
	global_store_dwordx2 v[102:103], v[106:107], off
	global_store_dwordx2 v[100:101], v[96:97], off offset:32
	global_store_dwordx2 v[102:103], v[96:97], off offset:32
	s_mov_b64 s[4:5], -1
	s_and_b64 vcc, exec, s[30:31]
	s_cbranch_vccz .LBB0_308
	v_mov_b32_e32 v131, v133
	v_add_u32_e32 v106, v250, v130
	ds_read_b128 v[96:99], v106 offset:32
	ds_read_b128 v[136:139], v106
	ds_bpermute_b32 v106, v155, v92
	ds_bpermute_b32 v107, v155, v93
	ds_bpermute_b32 v114, v155, v94
	ds_bpermute_b32 v115, v155, v95
	s_mov_b64 s[4:5], 0
	s_waitcnt lgkmcnt(0)
	v_pk_mul_f32 v[96:97], v[96:97], v[106:107]
	v_pk_mul_f32 v[98:99], v[98:99], v[114:115]
	v_cndmask_b32_e64 v97, v97, -v97, s[2:3]
	v_cndmask_b32_e64 v96, v96, -v96, s[2:3]
	v_cndmask_b32_e64 v99, v99, -v99, s[2:3]
	v_cndmask_b32_e64 v98, v98, -v98, s[2:3]
	v_pk_fma_f32 v[96:97], v[92:93], v[136:137], v[96:97]
	v_pk_fma_f32 v[98:99], v[94:95], v[138:139], v[98:99]

; DI uint2 pk4(float a, float b, float c, float d) { uint2 o; o.x = pk2(a, b); o.y = pk2(c, d); return o; }
; DI void phaseB(int wv0, PP p, unsigned char* smem) {
;     ...
;       epi256(wv0, acc, brow, bcol, [&](int ai, int bj, int m, int n, int row, int col0, f32x4& v) {
;         f32x4 r = v;
;         if (n == 0 && ropewave) {
;           const int pos = row & (S_ - 1), kq = ((lane >> 4) & 1) * 4;
;           const float4 c4 = *(const float4*)(rope + pos * 16 + kq), s4 = *(const float4*)(rope + pos * 16 + 8 + kq);
;           const float cc[4] = {c4.x, c4.y, c4.z, c4.w}, ss[4] = {s4.x, s4.y, s4.z, s4.w};
; #pragma unroll
;           for (int j = 0; j < 4; ++j) {
;             const float pr = __shfl_xor(v[j], 32);
;             r[j] = (lane & 32) ? (v[j] * cc[j] + pr * ss[j]) : (v[j] * cc[j] - pr * ss[j]);
;           }
;         }
;         *(uint2*)(QR + (size_t)row * 512 + col0) = pk4(v[0] * QSCALE, v[1] * QSCALE, v[2] * QSCALE, v[3] * QSCALE);
;         *(uint2*)(QO + (size_t)row * 512 + col0) = pk4(r[0] * QSCALE, r[1] * QSCALE, r[2] * QSCALE, r[3] * QSCALE);
.LBB0_310:
	v_pk_mul_f32 v[92:93], v[92:93], s[60:61] op_sel_hi:[1,0]
	v_pk_mul_f32 v[94:95], v[94:95], s[60:61] op_sel_hi:[1,0]
	v_cvt_pk_bf16_f32 v92, v92, v93
	v_cvt_pk_bf16_f32 v93, v94, v95
	global_store_dwordx2 v[124:125], v[92:93], off offset:256
	v_pk_mul_f32 v[92:93], v[96:97], s[60:61] op_sel_hi:[1,0]
	v_pk_mul_f32 v[94:95], v[98:99], s[60:61] op_sel_hi:[1,0]
	v_pk_mul_f32 v[88:89], v[88:89], s[60:61] op_sel_hi:[1,0]
	v_pk_mul_f32 v[90:91], v[90:91], s[60:61] op_sel_hi:[1,0]
	v_cvt_pk_bf16_f32 v92, v92, v93
	v_cvt_pk_bf16_f32 v93, v94, v95
	v_cvt_pk_bf16_f32 v88, v88, v89
	v_cvt_pk_bf16_f32 v89, v90, v91
	s_mov_b64 s[4:5], -1
	s_and_b64 vcc, exec, s[30:31]
	global_store_dwordx2 v[126:127], v[92:93], off offset:256
	global_store_dwordx2 v[124:125], v[88:89], off offset:288
	global_store_dwordx2 v[126:127], v[88:89], off offset:288
	s_cbranch_vccz .LBB0_312
	v_mov_b32_e32 v121, v133
	v_add_u32_e32 v92, v250, v120
	ds_read_b128 v[88:91], v92 offset:32
	s_nop 0
	ds_read_b128 v[92:95], v92
	ds_bpermute_b32 v96, v155, v84
	ds_bpermute_b32 v97, v155, v85
	ds_bpermute_b32 v98, v155, v86
	ds_bpermute_b32 v99, v155, v87
	s_mov_b64 s[4:5], 0
	s_waitcnt lgkmcnt(0)
	v_pk_mul_f32 v[88:89], v[88:89], v[96:97]
	v_pk_mul_f32 v[90:91], v[90:91], v[98:99]
	v_cndmask_b32_e64 v89, v89, -v89, s[2:3]
	v_cndmask_b32_e64 v88, v88, -v88, s[2:3]
	v_cndmask_b32_e64 v91, v91, -v91, s[2:3]
	v_cndmask_b32_e64 v90, v90, -v90, s[2:3]
	v_pk_fma_f32 v[88:89], v[84:85], v[92:93], v[88:89]
	v_pk_fma_f32 v[90:91], v[86:87], v[94:95], v[90:91]

; DI uint2 pk4(float a, float b, float c, float d) { uint2 o; o.x = pk2(a, b); o.y = pk2(c, d); return o; }
; DI void phaseB(int wv0, PP p, unsigned char* smem) {
;     ...
;       epi256(wv0, acc, brow, bcol, [&](int ai, int bj, int m, int n, int row, int col0, f32x4& v) {
;         f32x4 r = v;
;         if (n == 0 && ropewave) {
;           const int pos = row & (S_ - 1), kq = ((lane >> 4) & 1) * 4;
;           const float4 c4 = *(const float4*)(rope + pos * 16 + kq), s4 = *(const float4*)(rope + pos * 16 + 8 + kq);
;           const float cc[4] = {c4.x, c4.y, c4.z, c4.w}, ss[4] = {s4.x, s4.y, s4.z, s4.w};
; #pragma unroll
;           for (int j = 0; j < 4; ++j) {
;             const float pr = __shfl_xor(v[j], 32);
;             r[j] = (lane & 32) ? (v[j] * cc[j] + pr * ss[j]) : (v[j] * cc[j] - pr * ss[j]);
;           }
;         }
;         *(uint2*)(QR + (size_t)row * 512 + col0) = pk4(v[0] * QSCALE, v[1] * QSCALE, v[2] * QSCALE, v[3] * QSCALE);
;         *(uint2*)(QO + (size_t)row * 512 + col0) = pk4(r[0] * QSCALE, r[1] * QSCALE, r[2] * QSCALE, r[3] * QSCALE);
.LBB0_314:
	v_pk_mul_f32 v[84:85], v[84:85], s[60:61] op_sel_hi:[1,0]
	v_pk_mul_f32 v[86:87], v[86:87], s[60:61] op_sel_hi:[1,0]
	v_cvt_pk_bf16_f32 v84, v84, v85
	v_cvt_pk_bf16_f32 v85, v86, v87
	global_store_dwordx2 v[116:117], v[84:85], off offset:256
	v_pk_mul_f32 v[84:85], v[88:89], s[60:61] op_sel_hi:[1,0]
	v_pk_mul_f32 v[86:87], v[90:91], s[60:61] op_sel_hi:[1,0]
	v_pk_mul_f32 v[80:81], v[80:81], s[60:61] op_sel_hi:[1,0]
	v_pk_mul_f32 v[82:83], v[82:83], s[60:61] op_sel_hi:[1,0]
	v_cvt_pk_bf16_f32 v84, v84, v85
	v_cvt_pk_bf16_f32 v85, v86, v87
	v_cvt_pk_bf16_f32 v80, v80, v81
	v_cvt_pk_bf16_f32 v81, v82, v83
	global_store_dwordx2 v[118:119], v[84:85], off offset:256
	global_store_dwordx2 v[116:117], v[80:81], off offset:288
	global_store_dwordx2 v[118:119], v[80:81], off offset:288
	s_mov_b64 s[4:5], -1
	s_and_b64 vcc, exec, s[30:31]
	s_cbranch_vccz .LBB0_316
	v_mov_b32_e32 v113, v133
	v_add_u32_e32 v84, v250, v112
	ds_read_b128 v[80:83], v84 offset:32
	s_nop 0
	ds_read_b128 v[84:87], v84
	ds_bpermute_b32 v88, v155, v76
	ds_bpermute_b32 v89, v155, v77
	ds_bpermute_b32 v90, v155, v78
	ds_bpermute_b32 v91, v155, v79
	s_mov_b64 s[4:5], 0
	s_waitcnt lgkmcnt(0)
	v_pk_mul_f32 v[80:81], v[80:81], v[88:89]
	v_pk_mul_f32 v[82:83], v[82:83], v[90:91]
	v_cndmask_b32_e64 v81, v81, -v81, s[2:3]
	v_cndmask_b32_e64 v80, v80, -v80, s[2:3]
	v_cndmask_b32_e64 v83, v83, -v83, s[2:3]
	v_cndmask_b32_e64 v82, v82, -v82, s[2:3]
	v_pk_fma_f32 v[80:81], v[76:77], v[84:85], v[80:81]
	v_pk_fma_f32 v[82:83], v[78:79], v[86:87], v[82:83]

; DI uint2 pk4(float a, float b, float c, float d) { uint2 o; o.x = pk2(a, b); o.y = pk2(c, d); return o; }
; DI void phaseB(int wv0, PP p, unsigned char* smem) {
;     ...
;       epi256(wv0, acc, brow, bcol, [&](int ai, int bj, int m, int n, int row, int col0, f32x4& v) {
;         f32x4 r = v;
;         if (n == 0 && ropewave) {
;           const int pos = row & (S_ - 1), kq = ((lane >> 4) & 1) * 4;
;           const float4 c4 = *(const float4*)(rope + pos * 16 + kq), s4 = *(const float4*)(rope + pos * 16 + 8 + kq);
;           const float cc[4] = {c4.x, c4.y, c4.z, c4.w}, ss[4] = {s4.x, s4.y, s4.z, s4.w};
; #pragma unroll
;           for (int j = 0; j < 4; ++j) {
;             const float pr = __shfl_xor(v[j], 32);
;             r[j] = (lane & 32) ? (v[j] * cc[j] + pr * ss[j]) : (v[j] * cc[j] - pr * ss[j]);
;           }
;         }
;         *(uint2*)(QR + (size_t)row * 512 + col0) = pk4(v[0] * QSCALE, v[1] * QSCALE, v[2] * QSCALE, v[3] * QSCALE);
;         *(uint2*)(QO + (size_t)row * 512 + col0) = pk4(r[0] * QSCALE, r[1] * QSCALE, r[2] * QSCALE, r[3] * QSCALE);
.LBB0_318:
	v_pk_mul_f32 v[76:77], v[76:77], s[60:61] op_sel_hi:[1,0]
	v_pk_mul_f32 v[78:79], v[78:79], s[60:61] op_sel_hi:[1,0]
	v_cvt_pk_bf16_f32 v76, v76, v77
	v_cvt_pk_bf16_f32 v77, v78, v79
	global_store_dwordx2 v[108:109], v[76:77], off offset:256
	v_pk_mul_f32 v[76:77], v[80:81], s[60:61] op_sel_hi:[1,0]
	v_pk_mul_f32 v[78:79], v[82:83], s[60:61] op_sel_hi:[1,0]
	v_pk_mul_f32 v[72:73], v[72:73], s[60:61] op_sel_hi:[1,0]
	v_pk_mul_f32 v[74:75], v[74:75], s[60:61] op_sel_hi:[1,0]
	v_cvt_pk_bf16_f32 v76, v76, v77
	v_cvt_pk_bf16_f32 v77, v78, v79
	v_cvt_pk_bf16_f32 v72, v72, v73
	v_cvt_pk_bf16_f32 v73, v74, v75
	s_mov_b64 s[4:5], -1
	s_and_b64 vcc, exec, s[30:31]
	global_store_dwordx2 v[110:111], v[76:77], off offset:256
	global_store_dwordx2 v[108:109], v[72:73], off offset:288
	global_store_dwordx2 v[110:111], v[72:73], off offset:288
	s_cbranch_vccz .LBB0_320
	v_mov_b32_e32 v105, v133
	v_add_u32_e32 v76, v250, v104
	ds_read_b128 v[72:75], v76 offset:32
	s_nop 0
	ds_read_b128 v[76:79], v76
	ds_bpermute_b32 v80, v155, v68
	ds_bpermute_b32 v81, v155, v69
	ds_bpermute_b32 v82, v155, v70
	ds_bpermute_b32 v83, v155, v71
	s_mov_b64 s[4:5], 0
	s_waitcnt lgkmcnt(0)
	v_pk_mul_f32 v[72:73], v[72:73], v[80:81]
	v_pk_mul_f32 v[74:75], v[74:75], v[82:83]
	v_cndmask_b32_e64 v73, v73, -v73, s[2:3]
	v_cndmask_b32_e64 v72, v72, -v72, s[2:3]
	v_cndmask_b32_e64 v75, v75, -v75, s[2:3]
	v_cndmask_b32_e64 v74, v74, -v74, s[2:3]
	v_pk_fma_f32 v[72:73], v[68:69], v[76:77], v[72:73]
	v_pk_fma_f32 v[74:75], v[70:71], v[78:79], v[74:75]

; DI uint2 pk4(float a, float b, float c, float d) { uint2 o; o.x = pk2(a, b); o.y = pk2(c, d); return o; }
; DI void phaseB(int wv0, PP p, unsigned char* smem) {
;     ...
;       epi256(wv0, acc, brow, bcol, [&](int ai, int bj, int m, int n, int row, int col0, f32x4& v) {
;         f32x4 r = v;
;         if (n == 0 && ropewave) {
;           const int pos = row & (S_ - 1), kq = ((lane >> 4) & 1) * 4;
;           const float4 c4 = *(const float4*)(rope + pos * 16 + kq), s4 = *(const float4*)(rope + pos * 16 + 8 + kq);
;           const float cc[4] = {c4.x, c4.y, c4.z, c4.w}, ss[4] = {s4.x, s4.y, s4.z, s4.w};
; #pragma unroll
;           for (int j = 0; j < 4; ++j) {
;             const float pr = __shfl_xor(v[j], 32);
;             r[j] = (lane & 32) ? (v[j] * cc[j] + pr * ss[j]) : (v[j] * cc[j] - pr * ss[j]);
;           }
;         }
;         *(uint2*)(QR + (size_t)row * 512 + col0) = pk4(v[0] * QSCALE, v[1] * QSCALE, v[2] * QSCALE, v[3] * QSCALE);
;         *(uint2*)(QO + (size_t)row * 512 + col0) = pk4(r[0] * QSCALE, r[1] * QSCALE, r[2] * QSCALE, r[3] * QSCALE);
.LBB0_322:
	v_pk_mul_f32 v[68:69], v[68:69], s[60:61] op_sel_hi:[1,0]
	v_pk_mul_f32 v[70:71], v[70:71], s[60:61] op_sel_hi:[1,0]
	v_cvt_pk_bf16_f32 v68, v68, v69
	v_cvt_pk_bf16_f32 v69, v70, v71
	global_store_dwordx2 v[100:101], v[68:69], off offset:256
	v_pk_mul_f32 v[68:69], v[72:73], s[60:61] op_sel_hi:[1,0]
	v_pk_mul_f32 v[70:71], v[74:75], s[60:61] op_sel_hi:[1,0]
	v_pk_mul_f32 v[64:65], v[64:65], s[60:61] op_sel_hi:[1,0]
	v_pk_mul_f32 v[66:67], v[66:67], s[60:61] op_sel_hi:[1,0]
	v_cvt_pk_bf16_f32 v68, v68, v69
	v_cvt_pk_bf16_f32 v69, v70, v71
	v_cvt_pk_bf16_f32 v64, v64, v65
	v_cvt_pk_bf16_f32 v65, v66, v67
	global_store_dwordx2 v[102:103], v[68:69], off offset:256
	global_store_dwordx2 v[100:101], v[64:65], off offset:288
	global_store_dwordx2 v[102:103], v[64:65], off offset:288
	v_add_u32_e32 v66, 0x80, v128
	v_lshlrev_b32_e32 v64, 4, v66
	v_and_b32_e32 v64, 0x1fff0, v64
	s_mov_b64 s[4:5], -1
	s_and_b64 vcc, exec, s[30:31]
	v_lshlrev_b32_e32 v64, 2, v64
	s_cbranch_vccz .LBB0_324
	v_mov_b32_e32 v65, v133
	v_add_u32_e32 v72, v250, v64
	ds_read_b128 v[68:71], v72 offset:32
	s_nop 0
	ds_read_b128 v[72:75], v72
	ds_bpermute_b32 v76, v155, v60
	ds_bpermute_b32 v77, v155, v61
	ds_bpermute_b32 v78, v155, v62
	ds_bpermute_b32 v79, v155, v63
	s_mov_b64 s[4:5], 0
	s_waitcnt lgkmcnt(0)
	v_pk_mul_f32 v[68:69], v[68:69], v[76:77]
	v_pk_mul_f32 v[70:71], v[70:71], v[78:79]
	v_cndmask_b32_e64 v69, v69, -v69, s[2:3]
	v_cndmask_b32_e64 v68, v68, -v68, s[2:3]
	v_cndmask_b32_e64 v71, v71, -v71, s[2:3]
	v_cndmask_b32_e64 v70, v70, -v70, s[2:3]
	v_pk_fma_f32 v[68:69], v[60:61], v[72:73], v[68:69]
	v_pk_fma_f32 v[70:71], v[62:63], v[74:75], v[70:71]

; DI uint2 pk4(float a, float b, float c, float d) { uint2 o; o.x = pk2(a, b); o.y = pk2(c, d); return o; }
; DI void phaseB(int wv0, PP p, unsigned char* smem) {
;     ...
;       epi256(wv0, acc, brow, bcol, [&](int ai, int bj, int m, int n, int row, int col0, f32x4& v) {
;         f32x4 r = v;
;         if (n == 0 && ropewave) {
;           const int pos = row & (S_ - 1), kq = ((lane >> 4) & 1) * 4;
;           const float4 c4 = *(const float4*)(rope + pos * 16 + kq), s4 = *(const float4*)(rope + pos * 16 + 8 + kq);
;           const float cc[4] = {c4.x, c4.y, c4.z, c4.w}, ss[4] = {s4.x, s4.y, s4.z, s4.w};
; #pragma unroll
;           for (int j = 0; j < 4; ++j) {
;             const float pr = __shfl_xor(v[j], 32);
;             r[j] = (lane & 32) ? (v[j] * cc[j] + pr * ss[j]) : (v[j] * cc[j] - pr * ss[j]);
;           }
;         }
;         *(uint2*)(QR + (size_t)row * 512 + col0) = pk4(v[0] * QSCALE, v[1] * QSCALE, v[2] * QSCALE, v[3] * QSCALE);
;         *(uint2*)(QO + (size_t)row * 512 + col0) = pk4(r[0] * QSCALE, r[1] * QSCALE, r[2] * QSCALE, r[3] * QSCALE);
.LBB0_326:
	v_ashrrev_i32_e32 v67, 31, v66
	v_pk_mul_f32 v[62:63], v[62:63], s[60:61] op_sel_hi:[1,0]
	v_pk_mul_f32 v[60:61], v[60:61], s[60:61] op_sel_hi:[1,0]
	v_cvt_pk_bf16_f32 v73, v62, v63
	v_lshlrev_b64 v[62:63], 10, v[66:67]
	v_cvt_pk_bf16_f32 v72, v60, v61
	v_lshl_add_u64 v[60:61], s[26:27], 0, v[62:63]
	v_pk_mul_f32 v[66:67], v[68:69], s[60:61] op_sel_hi:[1,0]
	v_pk_mul_f32 v[68:69], v[70:71], s[60:61] op_sel_hi:[1,0]
	v_lshl_add_u64 v[62:63], s[28:29], 0, v[62:63]
	v_pk_mul_f32 v[56:57], v[56:57], s[60:61] op_sel_hi:[1,0]
	v_pk_mul_f32 v[58:59], v[58:59], s[60:61] op_sel_hi:[1,0]
	v_lshl_add_u64 v[60:61], v[60:61], 0, v[132:133]
	v_cvt_pk_bf16_f32 v66, v66, v67
	v_cvt_pk_bf16_f32 v67, v68, v69
	v_lshl_add_u64 v[62:63], v[62:63], 0, v[132:133]
	v_cvt_pk_bf16_f32 v56, v56, v57
	v_cvt_pk_bf16_f32 v57, v58, v59
	v_add_u32_e32 v58, 0x90, v128
	global_store_dwordx2 v[60:61], v[72:73], off
	global_store_dwordx2 v[62:63], v[66:67], off
	global_store_dwordx2 v[60:61], v[56:57], off offset:32
	global_store_dwordx2 v[62:63], v[56:57], off offset:32
	v_lshlrev_b32_e32 v56, 4, v58
	v_and_b32_e32 v56, 0x1fff0, v56
	s_mov_b64 s[4:5], -1
	s_and_b64 vcc, exec, s[30:31]
	v_lshlrev_b32_e32 v56, 2, v56
	s_cbranch_vccz .LBB0_328
	v_mov_b32_e32 v57, v133
	v_add_u32_e32 v70, v250, v56
	ds_read_b128 v[66:69], v70 offset:32
	s_nop 0
	ds_read_b128 v[70:73], v70
	ds_bpermute_b32 v74, v155, v52
	ds_bpermute_b32 v75, v155, v53
	ds_bpermute_b32 v76, v155, v54
	ds_bpermute_b32 v77, v155, v55
	s_mov_b64 s[4:5], 0
	s_waitcnt lgkmcnt(0)
	v_pk_mul_f32 v[66:67], v[66:67], v[74:75]
	v_pk_mul_f32 v[68:69], v[68:69], v[76:77]
	v_cndmask_b32_e64 v67, v67, -v67, s[2:3]
	v_cndmask_b32_e64 v66, v66, -v66, s[2:3]
	v_cndmask_b32_e64 v69, v69, -v69, s[2:3]
	v_cndmask_b32_e64 v68, v68, -v68, s[2:3]
	v_pk_fma_f32 v[66:67], v[52:53], v[70:71], v[66:67]
	v_pk_fma_f32 v[68:69], v[54:55], v[72:73], v[68:69]

; DI uint2 pk4(float a, float b, float c, float d) { uint2 o; o.x = pk2(a, b); o.y = pk2(c, d); return o; }
; DI void phaseB(int wv0, PP p, unsigned char* smem) {
;     ...
;       epi256(wv0, acc, brow, bcol, [&](int ai, int bj, int m, int n, int row, int col0, f32x4& v) {
;         f32x4 r = v;
;         if (n == 0 && ropewave) {
;           const int pos = row & (S_ - 1), kq = ((lane >> 4) & 1) * 4;
;           const float4 c4 = *(const float4*)(rope + pos * 16 + kq), s4 = *(const float4*)(rope + pos * 16 + 8 + kq);
;           const float cc[4] = {c4.x, c4.y, c4.z, c4.w}, ss[4] = {s4.x, s4.y, s4.z, s4.w};
; #pragma unroll
;           for (int j = 0; j < 4; ++j) {
;             const float pr = __shfl_xor(v[j], 32);
;             r[j] = (lane & 32) ? (v[j] * cc[j] + pr * ss[j]) : (v[j] * cc[j] - pr * ss[j]);
;           }
;         }
;         *(uint2*)(QR + (size_t)row * 512 + col0) = pk4(v[0] * QSCALE, v[1] * QSCALE, v[2] * QSCALE, v[3] * QSCALE);
;         *(uint2*)(QO + (size_t)row * 512 + col0) = pk4(r[0] * QSCALE, r[1] * QSCALE, r[2] * QSCALE, r[3] * QSCALE);
.LBB0_330:
	v_ashrrev_i32_e32 v59, 31, v58
	v_pk_mul_f32 v[54:55], v[54:55], s[60:61] op_sel_hi:[1,0]
	v_pk_mul_f32 v[52:53], v[52:53], s[60:61] op_sel_hi:[1,0]
	v_cvt_pk_bf16_f32 v71, v54, v55
	v_lshlrev_b64 v[54:55], 10, v[58:59]
	v_cvt_pk_bf16_f32 v70, v52, v53
	v_lshl_add_u64 v[52:53], s[26:27], 0, v[54:55]
	v_pk_mul_f32 v[58:59], v[66:67], s[60:61] op_sel_hi:[1,0]
	v_pk_mul_f32 v[66:67], v[68:69], s[60:61] op_sel_hi:[1,0]
	v_lshl_add_u64 v[54:55], s[28:29], 0, v[54:55]
	v_pk_mul_f32 v[48:49], v[48:49], s[60:61] op_sel_hi:[1,0]
	v_pk_mul_f32 v[50:51], v[50:51], s[60:61] op_sel_hi:[1,0]
	v_lshl_add_u64 v[52:53], v[52:53], 0, v[132:133]
	v_cvt_pk_bf16_f32 v58, v58, v59
	v_cvt_pk_bf16_f32 v59, v66, v67
	v_lshl_add_u64 v[54:55], v[54:55], 0, v[132:133]
	v_cvt_pk_bf16_f32 v48, v48, v49
	v_cvt_pk_bf16_f32 v49, v50, v51
	global_store_dwordx2 v[52:53], v[70:71], off
	global_store_dwordx2 v[54:55], v[58:59], off
	global_store_dwordx2 v[52:53], v[48:49], off offset:32
	global_store_dwordx2 v[54:55], v[48:49], off offset:32
	v_add_u32_e32 v50, 0xa0, v128
	v_lshlrev_b32_e32 v48, 4, v50
	v_and_b32_e32 v48, 0x1fff0, v48
	s_mov_b64 s[4:5], -1
	s_and_b64 vcc, exec, s[30:31]
	v_lshlrev_b32_e32 v48, 2, v48
	s_cbranch_vccz .LBB0_332
	v_mov_b32_e32 v49, v133
	v_add_u32_e32 v58, v250, v48
	ds_read_b128 v[66:69], v58 offset:32
	ds_read_b128 v[70:73], v58
	ds_bpermute_b32 v58, v155, v44
	ds_bpermute_b32 v59, v155, v45
	ds_bpermute_b32 v74, v155, v46
	ds_bpermute_b32 v75, v155, v47
	s_mov_b64 s[4:5], 0
	s_waitcnt lgkmcnt(0)
	v_pk_mul_f32 v[58:59], v[66:67], v[58:59]
	v_pk_mul_f32 v[66:67], v[68:69], v[74:75]
	v_cndmask_b32_e64 v59, v59, -v59, s[2:3]
	v_cndmask_b32_e64 v58, v58, -v58, s[2:3]
	v_cndmask_b32_e64 v67, v67, -v67, s[2:3]
	v_cndmask_b32_e64 v66, v66, -v66, s[2:3]
	v_pk_fma_f32 v[58:59], v[44:45], v[70:71], v[58:59]
	v_pk_fma_f32 v[66:67], v[46:47], v[72:73], v[66:67]

; DI uint2 pk4(float a, float b, float c, float d) { uint2 o; o.x = pk2(a, b); o.y = pk2(c, d); return o; }
; DI void phaseB(int wv0, PP p, unsigned char* smem) {
;     ...
;       epi256(wv0, acc, brow, bcol, [&](int ai, int bj, int m, int n, int row, int col0, f32x4& v) {
;         f32x4 r = v;
;         if (n == 0 && ropewave) {
;           const int pos = row & (S_ - 1), kq = ((lane >> 4) & 1) * 4;
;           const float4 c4 = *(const float4*)(rope + pos * 16 + kq), s4 = *(const float4*)(rope + pos * 16 + 8 + kq);
;           const float cc[4] = {c4.x, c4.y, c4.z, c4.w}, ss[4] = {s4.x, s4.y, s4.z, s4.w};
; #pragma unroll
;           for (int j = 0; j < 4; ++j) {
;             const float pr = __shfl_xor(v[j], 32);
;             r[j] = (lane & 32) ? (v[j] * cc[j] + pr * ss[j]) : (v[j] * cc[j] - pr * ss[j]);
;           }
;         }
;         *(uint2*)(QR + (size_t)row * 512 + col0) = pk4(v[0] * QSCALE, v[1] * QSCALE, v[2] * QSCALE, v[3] * QSCALE);
;         *(uint2*)(QO + (size_t)row * 512 + col0) = pk4(r[0] * QSCALE, r[1] * QSCALE, r[2] * QSCALE, r[3] * QSCALE);
.LBB0_334:
	v_ashrrev_i32_e32 v51, 31, v50
	v_pk_mul_f32 v[46:47], v[46:47], s[60:61] op_sel_hi:[1,0]
	v_pk_mul_f32 v[44:45], v[44:45], s[60:61] op_sel_hi:[1,0]
	v_cvt_pk_bf16_f32 v69, v46, v47
	v_lshlrev_b64 v[46:47], 10, v[50:51]
	v_cvt_pk_bf16_f32 v68, v44, v45
	v_lshl_add_u64 v[44:45], s[26:27], 0, v[46:47]
	v_pk_mul_f32 v[50:51], v[58:59], s[60:61] op_sel_hi:[1,0]
	v_pk_mul_f32 v[58:59], v[66:67], s[60:61] op_sel_hi:[1,0]
	v_lshl_add_u64 v[46:47], s[28:29], 0, v[46:47]
	v_pk_mul_f32 v[40:41], v[40:41], s[60:61] op_sel_hi:[1,0]
	v_pk_mul_f32 v[42:43], v[42:43], s[60:61] op_sel_hi:[1,0]
	v_lshl_add_u64 v[44:45], v[44:45], 0, v[132:133]
	v_cvt_pk_bf16_f32 v50, v50, v51
	v_cvt_pk_bf16_f32 v51, v58, v59
	v_lshl_add_u64 v[46:47], v[46:47], 0, v[132:133]
	v_cvt_pk_bf16_f32 v40, v40, v41
	v_cvt_pk_bf16_f32 v41, v42, v43
	v_add_u32_e32 v42, 0xb0, v128
	global_store_dwordx2 v[44:45], v[68:69], off
	global_store_dwordx2 v[46:47], v[50:51], off
	global_store_dwordx2 v[44:45], v[40:41], off offset:32
	global_store_dwordx2 v[46:47], v[40:41], off offset:32
	v_lshlrev_b32_e32 v40, 4, v42
	v_and_b32_e32 v40, 0x1fff0, v40
	s_mov_b64 s[4:5], -1
	s_and_b64 vcc, exec, s[30:31]
	v_lshlrev_b32_e32 v40, 2, v40
	s_cbranch_vccz .LBB0_336
	v_mov_b32_e32 v41, v133
	v_add_u32_e32 v50, v250, v40
	ds_read_b128 v[66:69], v50 offset:32
	ds_read_b128 v[70:73], v50
	ds_bpermute_b32 v50, v155, v36
	ds_bpermute_b32 v51, v155, v37
	ds_bpermute_b32 v58, v155, v38
	ds_bpermute_b32 v59, v155, v39
	s_mov_b64 s[4:5], 0
	s_waitcnt lgkmcnt(0)
	v_pk_mul_f32 v[50:51], v[66:67], v[50:51]
	v_pk_mul_f32 v[58:59], v[68:69], v[58:59]
	v_cndmask_b32_e64 v51, v51, -v51, s[2:3]
	v_cndmask_b32_e64 v50, v50, -v50, s[2:3]
	v_cndmask_b32_e64 v59, v59, -v59, s[2:3]
	v_cndmask_b32_e64 v58, v58, -v58, s[2:3]
	v_pk_fma_f32 v[50:51], v[36:37], v[70:71], v[50:51]
	v_pk_fma_f32 v[58:59], v[38:39], v[72:73], v[58:59]

; DI uint2 pk4(float a, float b, float c, float d) { uint2 o; o.x = pk2(a, b); o.y = pk2(c, d); return o; }
; DI void phaseB(int wv0, PP p, unsigned char* smem) {
;     ...
;       epi256(wv0, acc, brow, bcol, [&](int ai, int bj, int m, int n, int row, int col0, f32x4& v) {
;         f32x4 r = v;
;         if (n == 0 && ropewave) {
;           const int pos = row & (S_ - 1), kq = ((lane >> 4) & 1) * 4;
;           const float4 c4 = *(const float4*)(rope + pos * 16 + kq), s4 = *(const float4*)(rope + pos * 16 + 8 + kq);
;           const float cc[4] = {c4.x, c4.y, c4.z, c4.w}, ss[4] = {s4.x, s4.y, s4.z, s4.w};
; #pragma unroll
;           for (int j = 0; j < 4; ++j) {
;             const float pr = __shfl_xor(v[j], 32);
;             r[j] = (lane & 32) ? (v[j] * cc[j] + pr * ss[j]) : (v[j] * cc[j] - pr * ss[j]);
;           }
;         }
;         *(uint2*)(QR + (size_t)row * 512 + col0) = pk4(v[0] * QSCALE, v[1] * QSCALE, v[2] * QSCALE, v[3] * QSCALE);
;         *(uint2*)(QO + (size_t)row * 512 + col0) = pk4(r[0] * QSCALE, r[1] * QSCALE, r[2] * QSCALE, r[3] * QSCALE);
.LBB0_338:
	v_ashrrev_i32_e32 v43, 31, v42
	v_pk_mul_f32 v[38:39], v[38:39], s[60:61] op_sel_hi:[1,0]
	v_pk_mul_f32 v[36:37], v[36:37], s[60:61] op_sel_hi:[1,0]
	v_cvt_pk_bf16_f32 v67, v38, v39
	v_lshlrev_b64 v[38:39], 10, v[42:43]
	v_cvt_pk_bf16_f32 v66, v36, v37
	v_lshl_add_u64 v[36:37], s[26:27], 0, v[38:39]
	v_pk_mul_f32 v[42:43], v[50:51], s[60:61] op_sel_hi:[1,0]
	v_pk_mul_f32 v[50:51], v[58:59], s[60:61] op_sel_hi:[1,0]
	v_lshl_add_u64 v[38:39], s[28:29], 0, v[38:39]
	v_pk_mul_f32 v[32:33], v[32:33], s[60:61] op_sel_hi:[1,0]
	v_pk_mul_f32 v[34:35], v[34:35], s[60:61] op_sel_hi:[1,0]
	v_lshl_add_u64 v[36:37], v[36:37], 0, v[132:133]
	v_cvt_pk_bf16_f32 v42, v42, v43
	v_cvt_pk_bf16_f32 v43, v50, v51
	v_lshl_add_u64 v[38:39], v[38:39], 0, v[132:133]
	v_cvt_pk_bf16_f32 v32, v32, v33
	v_cvt_pk_bf16_f32 v33, v34, v35
	global_store_dwordx2 v[36:37], v[66:67], off
	global_store_dwordx2 v[38:39], v[42:43], off
	global_store_dwordx2 v[36:37], v[32:33], off offset:32
	global_store_dwordx2 v[38:39], v[32:33], off offset:32
	s_mov_b64 s[4:5], -1
	s_and_b64 vcc, exec, s[30:31]
	s_cbranch_vccz .LBB0_340
	v_mov_b32_e32 v65, v133
	v_add_u32_e32 v42, v250, v64
	ds_read_b128 v[32:35], v42 offset:32
	ds_read_b128 v[64:67], v42
	ds_bpermute_b32 v42, v155, v28
	ds_bpermute_b32 v43, v155, v29
	ds_bpermute_b32 v50, v155, v30
	ds_bpermute_b32 v51, v155, v31
	s_mov_b64 s[4:5], 0
	s_waitcnt lgkmcnt(0)
	v_pk_mul_f32 v[32:33], v[32:33], v[42:43]
	v_pk_mul_f32 v[34:35], v[34:35], v[50:51]
	v_cndmask_b32_e64 v33, v33, -v33, s[2:3]
	v_cndmask_b32_e64 v32, v32, -v32, s[2:3]
	v_cndmask_b32_e64 v35, v35, -v35, s[2:3]
	v_cndmask_b32_e64 v34, v34, -v34, s[2:3]
	v_pk_fma_f32 v[32:33], v[28:29], v[64:65], v[32:33]
	v_pk_fma_f32 v[34:35], v[30:31], v[66:67], v[34:35]

; DI uint2 pk4(float a, float b, float c, float d) { uint2 o; o.x = pk2(a, b); o.y = pk2(c, d); return o; }
; DI void phaseB(int wv0, PP p, unsigned char* smem) {
;     ...
;       epi256(wv0, acc, brow, bcol, [&](int ai, int bj, int m, int n, int row, int col0, f32x4& v) {
;         f32x4 r = v;
;         if (n == 0 && ropewave) {
;           const int pos = row & (S_ - 1), kq = ((lane >> 4) & 1) * 4;
;           const float4 c4 = *(const float4*)(rope + pos * 16 + kq), s4 = *(const float4*)(rope + pos * 16 + 8 + kq);
;           const float cc[4] = {c4.x, c4.y, c4.z, c4.w}, ss[4] = {s4.x, s4.y, s4.z, s4.w};
; #pragma unroll
;           for (int j = 0; j < 4; ++j) {
;             const float pr = __shfl_xor(v[j], 32);
;             r[j] = (lane & 32) ? (v[j] * cc[j] + pr * ss[j]) : (v[j] * cc[j] - pr * ss[j]);
;           }
;         }
;         *(uint2*)(QR + (size_t)row * 512 + col0) = pk4(v[0] * QSCALE, v[1] * QSCALE, v[2] * QSCALE, v[3] * QSCALE);
;         *(uint2*)(QO + (size_t)row * 512 + col0) = pk4(r[0] * QSCALE, r[1] * QSCALE, r[2] * QSCALE, r[3] * QSCALE);
.LBB0_342:
	v_pk_mul_f32 v[28:29], v[28:29], s[60:61] op_sel_hi:[1,0]
	v_pk_mul_f32 v[30:31], v[30:31], s[60:61] op_sel_hi:[1,0]
	v_cvt_pk_bf16_f32 v28, v28, v29
	v_cvt_pk_bf16_f32 v29, v30, v31
	global_store_dwordx2 v[60:61], v[28:29], off offset:256
	v_pk_mul_f32 v[28:29], v[32:33], s[60:61] op_sel_hi:[1,0]
	v_pk_mul_f32 v[30:31], v[34:35], s[60:61] op_sel_hi:[1,0]
	v_pk_mul_f32 v[24:25], v[24:25], s[60:61] op_sel_hi:[1,0]
	v_pk_mul_f32 v[26:27], v[26:27], s[60:61] op_sel_hi:[1,0]
	v_cvt_pk_bf16_f32 v28, v28, v29
	v_cvt_pk_bf16_f32 v29, v30, v31
	v_cvt_pk_bf16_f32 v24, v24, v25
	v_cvt_pk_bf16_f32 v25, v26, v27
	s_mov_b64 s[4:5], -1
	s_and_b64 vcc, exec, s[30:31]
	global_store_dwordx2 v[62:63], v[28:29], off offset:256
	global_store_dwordx2 v[60:61], v[24:25], off offset:288
	global_store_dwordx2 v[62:63], v[24:25], off offset:288
	s_cbranch_vccz .LBB0_344
	v_mov_b32_e32 v57, v133
	v_add_u32_e32 v28, v250, v56
	ds_read_b128 v[24:27], v28 offset:32
	s_nop 0
	ds_read_b128 v[28:31], v28
	ds_bpermute_b32 v32, v155, v20
	ds_bpermute_b32 v33, v155, v21
	ds_bpermute_b32 v34, v155, v22
	ds_bpermute_b32 v35, v155, v23
	s_mov_b64 s[4:5], 0
	s_waitcnt lgkmcnt(0)
	v_pk_mul_f32 v[24:25], v[24:25], v[32:33]
	v_pk_mul_f32 v[26:27], v[26:27], v[34:35]
	v_cndmask_b32_e64 v25, v25, -v25, s[2:3]
	v_cndmask_b32_e64 v24, v24, -v24, s[2:3]
	v_cndmask_b32_e64 v27, v27, -v27, s[2:3]
	v_cndmask_b32_e64 v26, v26, -v26, s[2:3]
	v_pk_fma_f32 v[24:25], v[20:21], v[28:29], v[24:25]
	v_pk_fma_f32 v[26:27], v[22:23], v[30:31], v[26:27]

; DI uint2 pk4(float a, float b, float c, float d) { uint2 o; o.x = pk2(a, b); o.y = pk2(c, d); return o; }
; DI void phaseB(int wv0, PP p, unsigned char* smem) {
;     ...
;       epi256(wv0, acc, brow, bcol, [&](int ai, int bj, int m, int n, int row, int col0, f32x4& v) {
;         f32x4 r = v;
;         if (n == 0 && ropewave) {
;           const int pos = row & (S_ - 1), kq = ((lane >> 4) & 1) * 4;
;           const float4 c4 = *(const float4*)(rope + pos * 16 + kq), s4 = *(const float4*)(rope + pos * 16 + 8 + kq);
;           const float cc[4] = {c4.x, c4.y, c4.z, c4.w}, ss[4] = {s4.x, s4.y, s4.z, s4.w};
; #pragma unroll
;           for (int j = 0; j < 4; ++j) {
;             const float pr = __shfl_xor(v[j], 32);
;             r[j] = (lane & 32) ? (v[j] * cc[j] + pr * ss[j]) : (v[j] * cc[j] - pr * ss[j]);
;           }
;         }
;         *(uint2*)(QR + (size_t)row * 512 + col0) = pk4(v[0] * QSCALE, v[1] * QSCALE, v[2] * QSCALE, v[3] * QSCALE);
;         *(uint2*)(QO + (size_t)row * 512 + col0) = pk4(r[0] * QSCALE, r[1] * QSCALE, r[2] * QSCALE, r[3] * QSCALE);
.LBB0_346:
	v_pk_mul_f32 v[20:21], v[20:21], s[60:61] op_sel_hi:[1,0]
	v_pk_mul_f32 v[22:23], v[22:23], s[60:61] op_sel_hi:[1,0]
	v_cvt_pk_bf16_f32 v20, v20, v21
	v_cvt_pk_bf16_f32 v21, v22, v23
	global_store_dwordx2 v[52:53], v[20:21], off offset:256
	v_pk_mul_f32 v[20:21], v[24:25], s[60:61] op_sel_hi:[1,0]
	v_pk_mul_f32 v[22:23], v[26:27], s[60:61] op_sel_hi:[1,0]
	v_pk_mul_f32 v[16:17], v[16:17], s[60:61] op_sel_hi:[1,0]
	v_pk_mul_f32 v[18:19], v[18:19], s[60:61] op_sel_hi:[1,0]
	v_cvt_pk_bf16_f32 v20, v20, v21
	v_cvt_pk_bf16_f32 v21, v22, v23
	v_cvt_pk_bf16_f32 v16, v16, v17
	v_cvt_pk_bf16_f32 v17, v18, v19
	global_store_dwordx2 v[54:55], v[20:21], off offset:256
	global_store_dwordx2 v[52:53], v[16:17], off offset:288
	global_store_dwordx2 v[54:55], v[16:17], off offset:288
	s_mov_b64 s[4:5], -1
	s_and_b64 vcc, exec, s[30:31]
	s_cbranch_vccz .LBB0_348
	v_mov_b32_e32 v49, v133
	v_add_u32_e32 v20, v250, v48
	ds_read_b128 v[16:19], v20 offset:32
	s_nop 0
	ds_read_b128 v[20:23], v20
	ds_bpermute_b32 v24, v155, v12
	ds_bpermute_b32 v25, v155, v13
	ds_bpermute_b32 v26, v155, v14
	ds_bpermute_b32 v27, v155, v15
	s_mov_b64 s[4:5], 0
	s_waitcnt lgkmcnt(0)
	v_pk_mul_f32 v[16:17], v[16:17], v[24:25]
	v_pk_mul_f32 v[18:19], v[18:19], v[26:27]
	v_cndmask_b32_e64 v17, v17, -v17, s[2:3]
	v_cndmask_b32_e64 v16, v16, -v16, s[2:3]
	v_cndmask_b32_e64 v19, v19, -v19, s[2:3]
	v_cndmask_b32_e64 v18, v18, -v18, s[2:3]
	v_pk_fma_f32 v[16:17], v[12:13], v[20:21], v[16:17]
	v_pk_fma_f32 v[18:19], v[14:15], v[22:23], v[18:19]

; DI uint2 pk4(float a, float b, float c, float d) { uint2 o; o.x = pk2(a, b); o.y = pk2(c, d); return o; }
; DI void phaseB(int wv0, PP p, unsigned char* smem) {
;     ...
;       epi256(wv0, acc, brow, bcol, [&](int ai, int bj, int m, int n, int row, int col0, f32x4& v) {
;         f32x4 r = v;
;         if (n == 0 && ropewave) {
;           const int pos = row & (S_ - 1), kq = ((lane >> 4) & 1) * 4;
;           const float4 c4 = *(const float4*)(rope + pos * 16 + kq), s4 = *(const float4*)(rope + pos * 16 + 8 + kq);
;           const float cc[4] = {c4.x, c4.y, c4.z, c4.w}, ss[4] = {s4.x, s4.y, s4.z, s4.w};
; #pragma unroll
;           for (int j = 0; j < 4; ++j) {
;             const float pr = __shfl_xor(v[j], 32);
;             r[j] = (lane & 32) ? (v[j] * cc[j] + pr * ss[j]) : (v[j] * cc[j] - pr * ss[j]);
;           }
;         }
;         *(uint2*)(QR + (size_t)row * 512 + col0) = pk4(v[0] * QSCALE, v[1] * QSCALE, v[2] * QSCALE, v[3] * QSCALE);
;         *(uint2*)(QO + (size_t)row * 512 + col0) = pk4(r[0] * QSCALE, r[1] * QSCALE, r[2] * QSCALE, r[3] * QSCALE);
.LBB0_350:
	v_pk_mul_f32 v[12:13], v[12:13], s[60:61] op_sel_hi:[1,0]
	v_pk_mul_f32 v[14:15], v[14:15], s[60:61] op_sel_hi:[1,0]
	v_cvt_pk_bf16_f32 v12, v12, v13
	v_cvt_pk_bf16_f32 v13, v14, v15
	global_store_dwordx2 v[44:45], v[12:13], off offset:256
	v_pk_mul_f32 v[12:13], v[16:17], s[60:61] op_sel_hi:[1,0]
	v_pk_mul_f32 v[14:15], v[18:19], s[60:61] op_sel_hi:[1,0]
	v_pk_mul_f32 v[8:9], v[8:9], s[60:61] op_sel_hi:[1,0]
	v_pk_mul_f32 v[10:11], v[10:11], s[60:61] op_sel_hi:[1,0]
	v_cvt_pk_bf16_f32 v12, v12, v13
	v_cvt_pk_bf16_f32 v13, v14, v15
	v_cvt_pk_bf16_f32 v8, v8, v9
	v_cvt_pk_bf16_f32 v9, v10, v11
	s_mov_b64 s[4:5], -1
	s_and_b64 vcc, exec, s[30:31]
	global_store_dwordx2 v[46:47], v[12:13], off offset:256
	global_store_dwordx2 v[44:45], v[8:9], off offset:288
	global_store_dwordx2 v[46:47], v[8:9], off offset:288
	s_cbranch_vccz .LBB0_352
	v_mov_b32_e32 v41, v133
	v_add_u32_e32 v12, v250, v40
	ds_read_b128 v[8:11], v12 offset:32
	s_nop 0
	ds_read_b128 v[12:15], v12
	ds_bpermute_b32 v16, v155, v4
	ds_bpermute_b32 v17, v155, v5
	ds_bpermute_b32 v18, v155, v6
	ds_bpermute_b32 v19, v155, v7
	s_mov_b64 s[4:5], 0
	s_waitcnt lgkmcnt(0)
	v_pk_mul_f32 v[8:9], v[8:9], v[16:17]
	v_pk_mul_f32 v[10:11], v[10:11], v[18:19]
	v_cndmask_b32_e64 v9, v9, -v9, s[2:3]
	v_cndmask_b32_e64 v8, v8, -v8, s[2:3]
	v_cndmask_b32_e64 v11, v11, -v11, s[2:3]
	v_cndmask_b32_e64 v10, v10, -v10, s[2:3]
	v_pk_fma_f32 v[8:9], v[4:5], v[12:13], v[8:9]
	v_pk_fma_f32 v[10:11], v[6:7], v[14:15], v[10:11]
